# RMS-norm of the SSM half of MIX folded into the out-proj GEMM (acc scaled by 1/rs after the attention half of K and by rs at the end, f32); PE read-modify-write pass over MIX removed
# speedup vs baseline: 1.0100x; 1.0077x over previous
; __device__ __forceinline__ float rsq(float x) { return __builtin_amdgcn_rsqf(x); }
; __device__ __forceinline__ float sum4(f32x4 v) { return (v[0] + v[1]) + (v[2] + v[3]); }
; template <class Epi, class Sched, bool ALIGN_EPI>
; __device__ __forceinline__ void gemm_phase(LAS unsigned char* lds, const Gemm g, const Sched& S, const Epi& E) {
;     ...
;         const bool has_next = S.next(ui + 1, nxt);
;         const char* nA = has_next ? (const char*)g.A + (size_t)nxt.pm * tstepA : cA; const char* nB = has_next ? (const char*)g.Bt + (size_t)nxt.pn * tstepB : cB;
; __global__ void __launch_bounds__(512, 2) fwd_kernel(Args args) {
;     ...
;                         for (int e = 0; e < 8; ++e) { const int row = pm * 256 + r0_ + 8 * e;
;                             const f32x4* sp = (const f32x4*)(stp + (size_t)row * 8);
;                             rsv[e] = rsq((sum4(sp[0]) + sum4(sp[1])) * (1.0f / SW) + EPS);
.LBB0_309:
	s_add_i32 s5, s5, 1
	s_load_dwordx2 s[100:101], s[0:1], 0xc8
	v_and_b32_e32 v160, 0xff, v209
	v_lshlrev_b32_e32 v161, 5, v160
	s_lshl_b32 vcc_lo, s77, 13
	s_waitcnt lgkmcnt(0)
	s_add_u32 s100, s100, 0x1200000
	s_addc_u32 s101, s101, 0
	s_add_u32 s100, s100, vcc_lo
	s_addc_u32 s101, s101, 0
	global_load_dwordx4 v[162:165], v161, s[100:101]
	global_load_dwordx4 v[166:169], v161, s[100:101] offset:16
	v_readlane_b32 s42, v254, 9
	s_mul_i32 s42, s5, s42
	s_waitcnt lgkmcnt(0)
	s_mul_hi_u32 s43, s5, s85
	s_add_i32 s43, s43, s42
	s_mul_i32 s42, s5, s85
	s_add_u32 s54, s42, s2
	s_addc_u32 s55, s43, s3
	v_mov_b64_e32 v[0:1], 0x3ff
	v_cmp_gt_i64_e32 vcc, s[54:55], v[0:1]
	v_cmp_lt_i64_e64 s[42:43], s[54:55], v[244:245]
	s_cbranch_vccnz .LBB0_315
	s_ashr_i32 s52, s54, 31
	s_lshr_b32 s52, s52, 29
	s_add_i32 s56, s54, s52
	s_and_b32 s52, s56, -8
	s_sub_i32 s57, s54, s52
	s_cmp_gt_i32 s57, -1
	s_mov_b64 s[54:55], -1
	s_cbranch_scc0 .LBB0_312
	s_lshl_b32 s58, s57, 7
	s_mov_b64 s[54:55], 0

; __device__ __forceinline__ float rsq(float x) { return __builtin_amdgcn_rsqf(x); }
; __device__ __forceinline__ float sum4(f32x4 v) { return (v[0] + v[1]) + (v[2] + v[3]); }
; template <class Epi, class Sched, bool ALIGN_EPI>
; __device__ __forceinline__ void gemm_phase(LAS unsigned char* lds, const Gemm g, const Sched& S, const Epi& E) {
;     ...
;         for (int a = 0; a < 2; ++a)
; #pragma unroll
;             for (int b = 0; b < 2; ++b)
; #pragma unroll
;                 for (int m = 0; m < 4; ++m)
; #pragma unroll
;                     for (int n = 0; n < 2; ++n) acc[a][b][m][n] = (f32x4){0.f, 0.f, 0.f, 0.f};
;         cur = nxt; cA = nA; cB = nB; ++ui;
; __global__ void __launch_bounds__(512, 2) fwd_kernel(Args args) {
;     ...
;                         for (int e = 0; e < 8; ++e) { const int row = pm * 256 + r0_ + 8 * e;
;                             const f32x4* sp = (const f32x4*)(stp + (size_t)row * 8);
;                             rsv[e] = rsq((sum4(sp[0]) + sum4(sp[1])) * (1.0f / SW) + EPS);
.LBB0_315:
	s_ashr_i32 s63, s62, 31
	s_lshl_b64 s[54:55], s[62:63], 19
	s_add_u32 s80, s33, s54
	s_addc_u32 s81, s51, s55
	s_and_b64 s[54:55], s[42:43], exec
	s_cselect_b32 s56, s81, s45
	s_cselect_b32 s57, s80, s44
	s_ashr_i32 s59, s58, 31
	s_lshl_b64 s[54:55], s[58:59], 19
	v_readlane_b32 s52, v255, 46
	s_add_u32 s84, s52, s54
	s_addc_u32 s85, s87, s55
	s_and_b64 s[54:55], s[42:43], exec
	s_cselect_b32 s59, s85, s47
	s_cselect_b32 s63, s84, s46
	s_add_u32 s44, s44, 0x40080
	s_addc_u32 s45, s45, 0
	s_add_u32 s64, s46, 0x100
	v_mov_b32_e32 v0, 0
	s_addc_u32 s65, s47, 0
	s_mov_b32 s92, -2
	v_mov_b32_e32 v1, v0
	v_mov_b32_e32 v2, v0
	v_mov_b32_e32 v3, v0
	v_mov_b32_e32 v4, v0
	v_mov_b32_e32 v5, v0
	v_mov_b32_e32 v6, v0
	v_mov_b32_e32 v7, v0
	v_mov_b32_e32 v12, v0
	v_mov_b32_e32 v13, v0
	v_mov_b32_e32 v14, v0
	v_mov_b32_e32 v15, v0
	v_mov_b32_e32 v20, v0
	v_mov_b32_e32 v21, v0
	v_mov_b32_e32 v22, v0
	v_mov_b32_e32 v23, v0
	v_mov_b32_e32 v28, v0
	v_mov_b32_e32 v29, v0
	v_mov_b32_e32 v30, v0
	v_mov_b32_e32 v31, v0
	v_mov_b32_e32 v36, v0
	v_mov_b32_e32 v37, v0
	v_mov_b32_e32 v38, v0
	v_mov_b32_e32 v39, v0
	v_mov_b32_e32 v48, v0
	v_mov_b32_e32 v49, v0
	v_mov_b32_e32 v50, v0
	v_mov_b32_e32 v51, v0
	v_mov_b32_e32 v52, v0
	v_mov_b32_e32 v53, v0
	v_mov_b32_e32 v54, v0
	v_mov_b32_e32 v55, v0
	v_mov_b32_e32 v8, v0
	v_mov_b32_e32 v9, v0
	v_mov_b32_e32 v10, v0
	v_mov_b32_e32 v11, v0
	v_mov_b32_e32 v16, v0
	v_mov_b32_e32 v17, v0
	v_mov_b32_e32 v18, v0
	v_mov_b32_e32 v19, v0
	v_mov_b32_e32 v24, v0
	v_mov_b32_e32 v25, v0
	v_mov_b32_e32 v26, v0
	v_mov_b32_e32 v27, v0
	v_mov_b32_e32 v32, v0
	v_mov_b32_e32 v33, v0
	v_mov_b32_e32 v34, v0
	v_mov_b32_e32 v35, v0
	v_mov_b32_e32 v40, v0
	v_mov_b32_e32 v41, v0
	v_mov_b32_e32 v42, v0
	v_mov_b32_e32 v43, v0
	v_mov_b32_e32 v44, v0
	v_mov_b32_e32 v45, v0
	v_mov_b32_e32 v46, v0
	v_mov_b32_e32 v47, v0
	v_mov_b32_e32 v56, v0
	v_mov_b32_e32 v57, v0
	v_mov_b32_e32 v58, v0
	v_mov_b32_e32 v59, v0
	v_mov_b32_e32 v60, v0
	v_mov_b32_e32 v61, v0
	v_mov_b32_e32 v62, v0
	v_mov_b32_e32 v63, v0
	v_mov_b32_e32 v64, v0
	v_mov_b32_e32 v65, v0
	v_mov_b32_e32 v66, v0
	v_mov_b32_e32 v67, v0
	v_mov_b32_e32 v68, v0
	v_mov_b32_e32 v69, v0
	v_mov_b32_e32 v70, v0
	v_mov_b32_e32 v71, v0
	v_mov_b32_e32 v76, v0
	v_mov_b32_e32 v77, v0
	v_mov_b32_e32 v78, v0
	v_mov_b32_e32 v79, v0
	v_mov_b32_e32 v84, v0
	v_mov_b32_e32 v85, v0
	v_mov_b32_e32 v86, v0
	v_mov_b32_e32 v87, v0
	v_mov_b32_e32 v92, v0
	v_mov_b32_e32 v93, v0
	v_mov_b32_e32 v94, v0
	v_mov_b32_e32 v95, v0
	v_mov_b32_e32 v100, v0
	v_mov_b32_e32 v101, v0
	v_mov_b32_e32 v102, v0
	v_mov_b32_e32 v103, v0
	v_mov_b32_e32 v120, v0
	v_mov_b32_e32 v121, v0
	v_mov_b32_e32 v122, v0
	v_mov_b32_e32 v123, v0
	v_mov_b32_e32 v124, v0
	v_mov_b32_e32 v125, v0
	v_mov_b32_e32 v126, v0
	v_mov_b32_e32 v127, v0
	v_mov_b32_e32 v72, v0
	v_mov_b32_e32 v73, v0
	v_mov_b32_e32 v74, v0
	v_mov_b32_e32 v75, v0
	v_mov_b32_e32 v80, v0
	v_mov_b32_e32 v81, v0
	v_mov_b32_e32 v82, v0
	v_mov_b32_e32 v83, v0
	v_mov_b32_e32 v88, v0
	v_mov_b32_e32 v89, v0
	v_mov_b32_e32 v90, v0
	v_mov_b32_e32 v91, v0
	v_mov_b32_e32 v96, v0
	v_mov_b32_e32 v97, v0
	v_mov_b32_e32 v98, v0
	v_mov_b32_e32 v99, v0
	v_mov_b32_e32 v108, v0
	v_mov_b32_e32 v109, v0
	v_mov_b32_e32 v110, v0
	v_mov_b32_e32 v111, v0
	v_mov_b32_e32 v116, v0
	v_mov_b32_e32 v117, v0
	v_mov_b32_e32 v118, v0
	v_mov_b32_e32 v119, v0
	v_mov_b32_e32 v128, v0
	v_mov_b32_e32 v129, v0
	v_mov_b32_e32 v130, v0
	v_mov_b32_e32 v131, v0
	v_mov_b32_e32 v132, v0
	v_mov_b32_e32 v133, v0
	v_mov_b32_e32 v134, v0
	v_mov_b32_e32 v135, v0
	s_and_b32 vcc_lo, s5, 1
	s_mul_i32 vcc_lo, vcc_lo, 0x3800
	s_add_i32 vcc_lo, vcc_lo, 0x20000
	v_lshl_add_u32 v161, v160, 2, vcc_lo
	s_waitcnt vmcnt(0)
	v_add_f32_e32 v170, v162, v163
	v_add_f32_e32 v171, v164, v165
	v_add_f32_e32 v170, v170, v171
	v_add_f32_e32 v171, v166, v167
	v_add_f32_e32 v172, v168, v169
	v_add_f32_e32 v171, v171, v172
	v_add_f32_e32 v170, v170, v171
	v_fmamk_f32 v170, v170, 0x3b000000, v241
	v_rsq_f32_e32 v170, v170
	s_nop 1
	ds_write_b32 v161, v170
.LBB0_316:
	s_cmp_lg_u32 s92, 6
	s_cbranch_scc1 .Lpf_noscale
	s_and_b32 vcc_lo, s5, 1
	s_mul_i32 vcc_lo, vcc_lo, 0x3800
	s_and_b32 vcc_hi, s40, 0x100
	s_add_i32 vcc_lo, vcc_lo, 0x20000
	s_add_i32 vcc_lo, vcc_lo, vcc_hi
	v_lshl_add_u32 v176, v211, 2, vcc_lo
	ds_read_b32 v160, v176
	ds_read_b32 v162, v176 offset:64
	ds_read_b32 v164, v176 offset:128
	ds_read_b32 v166, v176 offset:192
	ds_read_b32 v168, v176 offset:512
	ds_read_b32 v170, v176 offset:576
	ds_read_b32 v172, v176 offset:640
	ds_read_b32 v174, v176 offset:704
	s_waitcnt lgkmcnt(0)
; __device__ __forceinline__ unsigned cvt_pk_bf16(float lo, float hi) { const cvt_f32x2_t v = {lo, hi}; const cvt_bf16x2_t b = __builtin_convertvector(v, cvt_bf16x2_t); return __builtin_bit_cast(unsigned, b); }
; #define PG8_STAGE(bufoff, gbase, voff) do { _Pragma("unroll") for (int _i = 0; _i < 2; ++_i) \
;         __builtin_amdgcn_global_load_lds((const unsigned*)((const char*)(gbase) + (voff)[_i]), (LAS unsigned*)(lds + (bufoff) + ldsw + _i * 8192), 16, 0, 0); } while (0)
; #define PG8_LDA(dst, b, h) do { _Pragma("unroll") for (int m = 0; m < 4; ++m) _Pragma("unroll") for (int k = 0; k < 2; ++k) dst[m][k] = *(const LAS bf16x8*)(lds + PG8_SA(b, h) + aoff + m * 2048 + k * 1024); } while (0)
; #define PG8_LDB(dst, b, h) do { _Pragma("unroll") for (int n = 0; n < 2; ++n) _Pragma("unroll") for (int k = 0; k < 2; ++k) dst[n][k] = *(const LAS bf16x8*)(lds + PG8_SB(b, h) + boff + n * 2048 + k * 1024); } while (0)
; #define PG8_WAIT_V(n) asm volatile("s_waitcnt vmcnt(" #n ")" ::: "memory")
; #define PG8_WAIT_L(n) asm volatile("s_waitcnt lgkmcnt(" #n ")" ::: "memory")
; #define PG8_BAR __builtin_amdgcn_s_barrier()
; #define PG8_SCHED __builtin_amdgcn_sched_barrier(0)
; template <class Epi, class Sched, bool ALIGN_EPI>
; __device__ __forceinline__ void gemm_phase(LAS unsigned char* lds, const Gemm g, const Sched& S, const Epi& E) {
;     ...
;             const bool last = (t == nt - 2);
;             const char* a1 = cA + (size_t)(t + 1) * kstep;
;             const char* a2 = last ? nA : cA + (size_t)(t + 2) * kstep; const char* b2 = last ? nB : cB + (size_t)(t + 2) * kstep;
;             const char* a3 = a2 + kstep; const char* b3 = b2 + kstep;
;             PG8_LDB(B0, 0, 0); PG8_LDB(B1, 0, 1); PG8_SCHED; PG8_LDA(At, 0, 0); PG8_STAGE(PG8_SA(1, 1), a1 + hstepA, voffA);
;             PG8_WAIT_V(8); PG8_WAIT_L(0); PG8_BAR; PG8_MMA(0, 0, At, B0); PG8_MMA(0, 1, At, B1); PG8_BAR; PG8_SCHED;
; __global__ void __launch_bounds__(512, 2) fwd_kernel(Args args) {
;     ...
;                         for (int e = 0; e < 8; ++e) { const int row = pm * 256 + r0_ + 8 * e; const float rs = rsv[e]; u32x4 w = wv[e];
;                             w.x = cvt_pk_bf16(bf_lo(w.x) * rs, bf_hi(w.x) * rs); w.y = cvt_pk_bf16(bf_lo(w.y) * rs, bf_hi(w.y) * rs);
;                             w.z = cvt_pk_bf16(bf_lo(w.z) * rs, bf_hi(w.z) * rs); w.w = cvt_pk_bf16(bf_lo(w.w) * rs, bf_hi(w.w) * rs);
	v_rcp_f32_e32 v160, v160
	v_rcp_f32_e32 v162, v162
	v_rcp_f32_e32 v164, v164
	v_rcp_f32_e32 v166, v166
	v_rcp_f32_e32 v168, v168
	v_rcp_f32_e32 v170, v170
	v_rcp_f32_e32 v172, v172
	v_rcp_f32_e32 v174, v174
	s_nop 1
	v_pk_mul_f32 v[120:121], v[160:161], v[120:121] op_sel_hi:[0,1]
	v_pk_mul_f32 v[122:123], v[160:161], v[122:123] op_sel_hi:[0,1]
	v_pk_mul_f32 v[124:125], v[160:161], v[124:125] op_sel_hi:[0,1]
	v_pk_mul_f32 v[126:127], v[160:161], v[126:127] op_sel_hi:[0,1]
	v_pk_mul_f32 v[128:129], v[160:161], v[128:129] op_sel_hi:[0,1]
	v_pk_mul_f32 v[130:131], v[160:161], v[130:131] op_sel_hi:[0,1]
	v_pk_mul_f32 v[132:133], v[160:161], v[132:133] op_sel_hi:[0,1]
	v_pk_mul_f32 v[134:135], v[160:161], v[134:135] op_sel_hi:[0,1]
	v_pk_mul_f32 v[92:93], v[162:163], v[92:93] op_sel_hi:[0,1]
	v_pk_mul_f32 v[94:95], v[162:163], v[94:95] op_sel_hi:[0,1]
	v_pk_mul_f32 v[100:101], v[162:163], v[100:101] op_sel_hi:[0,1]
	v_pk_mul_f32 v[102:103], v[162:163], v[102:103] op_sel_hi:[0,1]
	v_pk_mul_f32 v[108:109], v[162:163], v[108:109] op_sel_hi:[0,1]
	v_pk_mul_f32 v[110:111], v[162:163], v[110:111] op_sel_hi:[0,1]
	v_pk_mul_f32 v[116:117], v[162:163], v[116:117] op_sel_hi:[0,1]
	v_pk_mul_f32 v[118:119], v[162:163], v[118:119] op_sel_hi:[0,1]
	v_pk_mul_f32 v[76:77], v[164:165], v[76:77] op_sel_hi:[0,1]
	v_pk_mul_f32 v[78:79], v[164:165], v[78:79] op_sel_hi:[0,1]
	v_pk_mul_f32 v[84:85], v[164:165], v[84:85] op_sel_hi:[0,1]
	v_pk_mul_f32 v[86:87], v[164:165], v[86:87] op_sel_hi:[0,1]
	v_pk_mul_f32 v[88:89], v[164:165], v[88:89] op_sel_hi:[0,1]
	v_pk_mul_f32 v[90:91], v[164:165], v[90:91] op_sel_hi:[0,1]
	v_pk_mul_f32 v[96:97], v[164:165], v[96:97] op_sel_hi:[0,1]
	v_pk_mul_f32 v[98:99], v[164:165], v[98:99] op_sel_hi:[0,1]
	v_pk_mul_f32 v[64:65], v[166:167], v[64:65] op_sel_hi:[0,1]
	v_pk_mul_f32 v[66:67], v[166:167], v[66:67] op_sel_hi:[0,1]
	v_pk_mul_f32 v[68:69], v[166:167], v[68:69] op_sel_hi:[0,1]
	v_pk_mul_f32 v[70:71], v[166:167], v[70:71] op_sel_hi:[0,1]
	v_pk_mul_f32 v[72:73], v[166:167], v[72:73] op_sel_hi:[0,1]
	v_pk_mul_f32 v[74:75], v[166:167], v[74:75] op_sel_hi:[0,1]
	v_pk_mul_f32 v[80:81], v[166:167], v[80:81] op_sel_hi:[0,1]
	v_pk_mul_f32 v[82:83], v[166:167], v[82:83] op_sel_hi:[0,1]
	v_pk_mul_f32 v[48:49], v[168:169], v[48:49] op_sel_hi:[0,1]
	v_pk_mul_f32 v[50:51], v[168:169], v[50:51] op_sel_hi:[0,1]
	v_pk_mul_f32 v[52:53], v[168:169], v[52:53] op_sel_hi:[0,1]
	v_pk_mul_f32 v[54:55], v[168:169], v[54:55] op_sel_hi:[0,1]
	v_pk_mul_f32 v[56:57], v[168:169], v[56:57] op_sel_hi:[0,1]
	v_pk_mul_f32 v[58:59], v[168:169], v[58:59] op_sel_hi:[0,1]
	v_pk_mul_f32 v[60:61], v[168:169], v[60:61] op_sel_hi:[0,1]
	v_pk_mul_f32 v[62:63], v[168:169], v[62:63] op_sel_hi:[0,1]
	v_pk_mul_f32 v[28:29], v[170:171], v[28:29] op_sel_hi:[0,1]
	v_pk_mul_f32 v[30:31], v[170:171], v[30:31] op_sel_hi:[0,1]
	v_pk_mul_f32 v[36:37], v[170:171], v[36:37] op_sel_hi:[0,1]
	v_pk_mul_f32 v[38:39], v[170:171], v[38:39] op_sel_hi:[0,1]
	v_pk_mul_f32 v[40:41], v[170:171], v[40:41] op_sel_hi:[0,1]
	v_pk_mul_f32 v[42:43], v[170:171], v[42:43] op_sel_hi:[0,1]
	v_pk_mul_f32 v[44:45], v[170:171], v[44:45] op_sel_hi:[0,1]
	v_pk_mul_f32 v[46:47], v[170:171], v[46:47] op_sel_hi:[0,1]
	v_pk_mul_f32 v[12:13], v[172:173], v[12:13] op_sel_hi:[0,1]
	v_pk_mul_f32 v[14:15], v[172:173], v[14:15] op_sel_hi:[0,1]
	v_pk_mul_f32 v[20:21], v[172:173], v[20:21] op_sel_hi:[0,1]
	v_pk_mul_f32 v[22:23], v[172:173], v[22:23] op_sel_hi:[0,1]
	v_pk_mul_f32 v[24:25], v[172:173], v[24:25] op_sel_hi:[0,1]
	v_pk_mul_f32 v[26:27], v[172:173], v[26:27] op_sel_hi:[0,1]
	v_pk_mul_f32 v[32:33], v[172:173], v[32:33] op_sel_hi:[0,1]
	v_pk_mul_f32 v[34:35], v[172:173], v[34:35] op_sel_hi:[0,1]
	v_pk_mul_f32 v[0:1], v[174:175], v[0:1] op_sel_hi:[0,1]
	v_pk_mul_f32 v[2:3], v[174:175], v[2:3] op_sel_hi:[0,1]
	v_pk_mul_f32 v[4:5], v[174:175], v[4:5] op_sel_hi:[0,1]
	v_pk_mul_f32 v[6:7], v[174:175], v[6:7] op_sel_hi:[0,1]
	v_pk_mul_f32 v[8:9], v[174:175], v[8:9] op_sel_hi:[0,1]
	v_pk_mul_f32 v[10:11], v[174:175], v[10:11] op_sel_hi:[0,1]
	v_pk_mul_f32 v[16:17], v[174:175], v[16:17] op_sel_hi:[0,1]
	v_pk_mul_f32 v[18:19], v[174:175], v[18:19] op_sel_hi:[0,1]
.Lpf_noscale:
	s_add_u32 s46, s44, 0xfffc0080
	s_addc_u32 s47, s45, -1
	s_add_i32 s52, 0, 0x10000
	s_cmp_eq_u32 s92, 12
	s_cselect_b32 s55, s56, s47
	s_cselect_b32 s54, s57, s46
	s_cselect_b32 s47, s59, s65
	s_cselect_b32 s46, s63, s64
	s_add_i32 s53, 0, 0x14000
	v_add_u32_e32 v140, s52, v247
	v_add_u32_e32 v156, s53, v247
	ds_read_b128 v[104:107], v140
	ds_read_b128 v[112:115], v140 offset:1024
	ds_read_b128 v[136:139], v140 offset:2048
	ds_read_b128 v[140:143], v140 offset:3072
	ds_read_b128 v[144:147], v156
	ds_read_b128 v[148:151], v156 offset:1024
	ds_read_b128 v[152:155], v156 offset:2048
	ds_read_b128 v[156:159], v156 offset:3072
	v_lshl_add_u64 v[194:195], s[44:45], 0, v[220:221]
	s_add_i32 m0, s48, 0xc000
	ds_read_b128 v[160:163], v248
	ds_read_b128 v[164:167], v248 offset:1024
	ds_read_b128 v[168:171], v248 offset:2048
	ds_read_b128 v[172:175], v248 offset:3072
	ds_read_b128 v[176:179], v248 offset:4096
	ds_read_b128 v[180:183], v248 offset:5120
	ds_read_b128 v[184:187], v248 offset:6144
	ds_read_b128 v[188:191], v248 offset:7168
	global_load_lds_dwordx4 v[194:195], off
	v_lshl_add_u64 v[194:195], s[44:45], 0, v[222:223]
	s_add_i32 m0, s48, 0xe000
	s_nop 0
	global_load_lds_dwordx4 v[194:195], off
	s_waitcnt vmcnt(8)
	s_waitcnt lgkmcnt(0)
	s_barrier
; #define PG8_STAGE(bufoff, gbase, voff) do { _Pragma("unroll") for (int _i = 0; _i < 2; ++_i) \
;         __builtin_amdgcn_global_load_lds((const unsigned*)((const char*)(gbase) + (voff)[_i]), (LAS unsigned*)(lds + (bufoff) + ldsw + _i * 8192), 16, 0, 0); } while (0)
; #define PG8_LDA(dst, b, h) do { _Pragma("unroll") for (int m = 0; m < 4; ++m) _Pragma("unroll") for (int k = 0; k < 2; ++k) dst[m][k] = *(const LAS bf16x8*)(lds + PG8_SA(b, h) + aoff + m * 2048 + k * 1024); } while (0)
; #define PG8_MMA(ai, bj, At, Bt) do { __builtin_amdgcn_s_setprio(1); _Pragma("unroll") for (int m = 0; m < 4; ++m) _Pragma("unroll") for (int n = 0; n < 2; ++n) _Pragma("unroll") for (int k = 0; k < 2; ++k) \
;         acc[ai][bj][m][n] = __builtin_amdgcn_mfma_f32_16x16x32_bf16(Bt[n][k], At[m][k], acc[ai][bj][m][n], 0, 0, 0); __builtin_amdgcn_s_setprio(0); } while (0)
; #define PG8_WAIT_V(n) asm volatile("s_waitcnt vmcnt(" #n ")" ::: "memory")
; #define PG8_WAIT_L(n) asm volatile("s_waitcnt lgkmcnt(" #n ")" ::: "memory")
; #define PG8_BAR __builtin_amdgcn_s_barrier()
; #define PG8_SCHED __builtin_amdgcn_sched_barrier(0)
; template <class Epi, class Sched, bool ALIGN_EPI>
; __device__ __forceinline__ void gemm_phase(LAS unsigned char* lds, const Gemm g, const Sched& S, const Epi& E) {
;     ...
;             PG8_WAIT_V(8); PG8_WAIT_L(0); PG8_BAR; PG8_MMA(0, 0, At, B0); PG8_MMA(0, 1, At, B1); PG8_BAR; PG8_SCHED;
;             PG8_LDA(At, 0, 1); PG8_STAGE(PG8_SB(0, 0), b2, voffB); PG8_STAGE(PG8_SB(0, 1), b2 + hstepB, voffB); PG8_STAGE(PG8_SA(0, 0), a2, voffA);
;             PG8_WAIT_V(8); PG8_WAIT_L(0); PG8_BAR; PG8_MMA(1, 0, At, B0); PG8_MMA(1, 1, At, B1); PG8_BAR; PG8_SCHED;
	s_setprio 1
	s_waitcnt lgkmcnt(0)
	v_mfma_f32_16x16x32_bf16 v[132:135], v[104:107], v[160:163], v[132:135]
	v_mfma_f32_16x16x32_bf16 v[128:131], v[136:139], v[160:163], v[128:131]
	v_mfma_f32_16x16x32_bf16 v[116:119], v[104:107], v[168:171], v[116:119]
	v_mfma_f32_16x16x32_bf16 v[108:111], v[136:139], v[168:171], v[108:111]
	v_mfma_f32_16x16x32_bf16 v[96:99], v[104:107], v[176:179], v[96:99]
	v_mfma_f32_16x16x32_bf16 v[88:91], v[136:139], v[176:179], v[88:91]
	v_mfma_f32_16x16x32_bf16 v[80:83], v[104:107], v[184:187], v[80:83]
	v_mfma_f32_16x16x32_bf16 v[72:75], v[136:139], v[184:187], v[72:75]
	v_mfma_f32_16x16x32_bf16 v[132:135], v[112:115], v[164:167], v[132:135]
	v_mfma_f32_16x16x32_bf16 v[128:131], v[140:143], v[164:167], v[128:131]
	v_mfma_f32_16x16x32_bf16 v[116:119], v[112:115], v[172:175], v[116:119]
	v_mfma_f32_16x16x32_bf16 v[108:111], v[140:143], v[172:175], v[108:111]
	v_mfma_f32_16x16x32_bf16 v[96:99], v[112:115], v[180:183], v[96:99]
	v_mfma_f32_16x16x32_bf16 v[88:91], v[140:143], v[180:183], v[88:91]
	v_mfma_f32_16x16x32_bf16 v[80:83], v[112:115], v[188:191], v[80:83]
	v_mfma_f32_16x16x32_bf16 v[72:75], v[140:143], v[188:191], v[72:75]
	s_setprio 0
	s_setprio 1
	v_mfma_f32_16x16x32_bf16 v[124:127], v[144:147], v[160:163], v[124:127]
	v_mfma_f32_16x16x32_bf16 v[120:123], v[152:155], v[160:163], v[120:123]
	v_mfma_f32_16x16x32_bf16 v[100:103], v[144:147], v[168:171], v[100:103]
	v_mfma_f32_16x16x32_bf16 v[92:95], v[152:155], v[168:171], v[92:95]
	v_mfma_f32_16x16x32_bf16 v[84:87], v[144:147], v[176:179], v[84:87]
	v_mfma_f32_16x16x32_bf16 v[76:79], v[152:155], v[176:179], v[76:79]
	v_mfma_f32_16x16x32_bf16 v[68:71], v[144:147], v[184:187], v[68:71]
	v_mfma_f32_16x16x32_bf16 v[64:67], v[152:155], v[184:187], v[64:67]
	v_mfma_f32_16x16x32_bf16 v[124:127], v[148:151], v[164:167], v[124:127]
	v_mfma_f32_16x16x32_bf16 v[120:123], v[156:159], v[164:167], v[120:123]
	v_mfma_f32_16x16x32_bf16 v[100:103], v[148:151], v[172:175], v[100:103]
	v_mfma_f32_16x16x32_bf16 v[92:95], v[156:159], v[172:175], v[92:95]
	v_mfma_f32_16x16x32_bf16 v[84:87], v[148:151], v[180:183], v[84:87]
	v_mfma_f32_16x16x32_bf16 v[76:79], v[156:159], v[180:183], v[76:79]
	v_mfma_f32_16x16x32_bf16 v[68:71], v[148:151], v[188:191], v[68:71]
	v_mfma_f32_16x16x32_bf16 v[64:67], v[156:159], v[188:191], v[64:67]
	s_setprio 0
	s_barrier
	s_add_i32 s52, s52, s50
	v_lshl_add_u64 v[194:195], s[46:47], 0, v[216:217]
	s_mov_b32 m0, s52
	ds_read_b128 v[160:163], v248 offset:16384
	ds_read_b128 v[164:167], v248 offset:17408
	ds_read_b128 v[168:171], v248 offset:18432
	ds_read_b128 v[172:175], v248 offset:19456
	ds_read_b128 v[176:179], v248 offset:20480
	ds_read_b128 v[180:183], v248 offset:21504
	ds_read_b128 v[184:187], v248 offset:22528
	ds_read_b128 v[188:191], v248 offset:23552
	global_load_lds_dwordx4 v[194:195], off
	s_add_i32 m0, s52, 0x2000
	s_add_u32 vcc_lo, s46, 0x40000
	v_lshl_add_u64 v[196:197], s[46:47], 0, v[212:213]
	s_addc_u32 vcc_hi, s47, 0
	s_add_i32 s52, s53, s50
	global_load_lds_dwordx4 v[196:197], off
	v_lshl_add_u64 v[198:199], vcc, 0, v[216:217]
	s_mov_b32 m0, s52
	v_lshl_add_u64 v[200:201], s[54:55], 0, v[214:215]
	global_load_lds_dwordx4 v[198:199], off
	v_lshl_add_u64 v[198:199], vcc, 0, v[212:213]
	s_add_i32 m0, s52, 0x2000
	s_nop 0
	global_load_lds_dwordx4 v[198:199], off
	v_lshl_add_u64 v[198:199], s[54:55], 0, v[218:219]
	s_mov_b32 m0, s48
	s_nop 0
	global_load_lds_dwordx4 v[198:199], off
	s_mov_b32 m0, s49
	s_nop 0
	global_load_lds_dwordx4 v[200:201], off
	s_waitcnt vmcnt(8)
	s_waitcnt lgkmcnt(0)
	s_barrier
	s_setprio 1
	s_waitcnt lgkmcnt(0)
	v_mfma_f32_16x16x32_bf16 v[60:63], v[104:107], v[160:163], v[60:63]
	v_mfma_f32_16x16x32_bf16 v[56:59], v[136:139], v[160:163], v[56:59]
	v_mfma_f32_16x16x32_bf16 v[44:47], v[104:107], v[168:171], v[44:47]
	v_mfma_f32_16x16x32_bf16 v[40:43], v[136:139], v[168:171], v[40:43]
	v_mfma_f32_16x16x32_bf16 v[32:35], v[104:107], v[176:179], v[32:35]
	v_mfma_f32_16x16x32_bf16 v[24:27], v[136:139], v[176:179], v[24:27]
	v_mfma_f32_16x16x32_bf16 v[16:19], v[104:107], v[184:187], v[16:19]
	v_mfma_f32_16x16x32_bf16 v[8:11], v[136:139], v[184:187], v[8:11]
	v_mfma_f32_16x16x32_bf16 v[60:63], v[112:115], v[164:167], v[60:63]
	v_mfma_f32_16x16x32_bf16 v[56:59], v[140:143], v[164:167], v[56:59]
	v_mfma_f32_16x16x32_bf16 v[44:47], v[112:115], v[172:175], v[44:47]
	v_mfma_f32_16x16x32_bf16 v[40:43], v[140:143], v[172:175], v[40:43]
	v_mfma_f32_16x16x32_bf16 v[32:35], v[112:115], v[180:183], v[32:35]
	v_mfma_f32_16x16x32_bf16 v[24:27], v[140:143], v[180:183], v[24:27]
	v_mfma_f32_16x16x32_bf16 v[16:19], v[112:115], v[188:191], v[16:19]
	v_mfma_f32_16x16x32_bf16 v[8:11], v[140:143], v[188:191], v[8:11]
	s_setprio 0
	s_setprio 1
	v_mfma_f32_16x16x32_bf16 v[52:55], v[144:147], v[160:163], v[52:55]
	v_mfma_f32_16x16x32_bf16 v[48:51], v[152:155], v[160:163], v[48:51]
	v_mfma_f32_16x16x32_bf16 v[36:39], v[144:147], v[168:171], v[36:39]
	v_mfma_f32_16x16x32_bf16 v[28:31], v[152:155], v[168:171], v[28:31]
	v_mfma_f32_16x16x32_bf16 v[20:23], v[144:147], v[176:179], v[20:23]
	v_mfma_f32_16x16x32_bf16 v[12:15], v[152:155], v[176:179], v[12:15]
	v_mfma_f32_16x16x32_bf16 v[4:7], v[144:147], v[184:187], v[4:7]
	v_mfma_f32_16x16x32_bf16 v[0:3], v[152:155], v[184:187], v[0:3]
	v_mfma_f32_16x16x32_bf16 v[52:55], v[148:151], v[164:167], v[52:55]
	v_mfma_f32_16x16x32_bf16 v[48:51], v[156:159], v[164:167], v[48:51]
	v_mfma_f32_16x16x32_bf16 v[36:39], v[148:151], v[172:175], v[36:39]
	v_mfma_f32_16x16x32_bf16 v[28:31], v[156:159], v[172:175], v[28:31]
	v_mfma_f32_16x16x32_bf16 v[20:23], v[148:151], v[180:183], v[20:23]
	v_mfma_f32_16x16x32_bf16 v[12:15], v[156:159], v[180:183], v[12:15]
	v_mfma_f32_16x16x32_bf16 v[4:7], v[148:151], v[188:191], v[4:7]
	v_mfma_f32_16x16x32_bf16 v[0:3], v[156:159], v[188:191], v[0:3]
	s_setprio 0
	s_barrier
; #define PG8_STAGE(bufoff, gbase, voff) do { _Pragma("unroll") for (int _i = 0; _i < 2; ++_i) \
;         __builtin_amdgcn_global_load_lds((const unsigned*)((const char*)(gbase) + (voff)[_i]), (LAS unsigned*)(lds + (bufoff) + ldsw + _i * 8192), 16, 0, 0); } while (0)
; #define PG8_LDA(dst, b, h) do { _Pragma("unroll") for (int m = 0; m < 4; ++m) _Pragma("unroll") for (int k = 0; k < 2; ++k) dst[m][k] = *(const LAS bf16x8*)(lds + PG8_SA(b, h) + aoff + m * 2048 + k * 1024); } while (0)
; #define PG8_LDB(dst, b, h) do { _Pragma("unroll") for (int n = 0; n < 2; ++n) _Pragma("unroll") for (int k = 0; k < 2; ++k) dst[n][k] = *(const LAS bf16x8*)(lds + PG8_SB(b, h) + boff + n * 2048 + k * 1024); } while (0)
; #define PG8_MMA(ai, bj, At, Bt) do { __builtin_amdgcn_s_setprio(1); _Pragma("unroll") for (int m = 0; m < 4; ++m) _Pragma("unroll") for (int n = 0; n < 2; ++n) _Pragma("unroll") for (int k = 0; k < 2; ++k) \
;         acc[ai][bj][m][n] = __builtin_amdgcn_mfma_f32_16x16x32_bf16(Bt[n][k], At[m][k], acc[ai][bj][m][n], 0, 0, 0); __builtin_amdgcn_s_setprio(0); } while (0)
; #define PG8_WAIT_V(n) asm volatile("s_waitcnt vmcnt(" #n ")" ::: "memory")
; #define PG8_WAIT_L(n) asm volatile("s_waitcnt lgkmcnt(" #n ")" ::: "memory")
; #define PG8_BAR __builtin_amdgcn_s_barrier()
; #define PG8_SCHED __builtin_amdgcn_sched_barrier(0)
; template <class Epi, class Sched, bool ALIGN_EPI>
; __device__ __forceinline__ void gemm_phase(LAS unsigned char* lds, const Gemm g, const Sched& S, const Epi& E) {
;     ...
;             PG8_LDB(B0, 1, 0); PG8_LDB(B1, 1, 1); PG8_SCHED; PG8_LDA(At, 1, 0); PG8_STAGE(PG8_SA(0, 1), a2 + hstepA, voffA);
;             PG8_WAIT_V(8); PG8_WAIT_L(0); PG8_BAR; PG8_MMA(0, 0, At, B0); PG8_MMA(0, 1, At, B1); PG8_BAR; PG8_SCHED;
;             PG8_LDA(At, 1, 1); PG8_STAGE(PG8_SB(1, 0), b3, voffB); PG8_STAGE(PG8_SB(1, 1), b3 + hstepB, voffB); PG8_STAGE(PG8_SA(1, 0), a3, voffA);
	s_add_i32 s52, 0, 0x18000
	s_add_i32 s53, 0, 0x1c000
	v_add_u32_e32 v140, s52, v247
	v_add_u32_e32 v156, s53, v247
	ds_read_b128 v[104:107], v140
	ds_read_b128 v[112:115], v140 offset:1024
	ds_read_b128 v[136:139], v140 offset:2048
	ds_read_b128 v[140:143], v140 offset:3072
	ds_read_b128 v[144:147], v156
	ds_read_b128 v[148:151], v156 offset:1024
	ds_read_b128 v[152:155], v156 offset:2048
	ds_read_b128 v[156:159], v156 offset:3072
	s_add_u32 s54, s54, 0x40000
	s_addc_u32 s55, s55, 0
	s_mov_b32 m0, s67
	v_lshl_add_u64 v[202:203], s[54:55], 0, v[218:219]
	ds_read_b128 v[160:163], v248 offset:32768
	ds_read_b128 v[164:167], v248 offset:33792
	ds_read_b128 v[168:171], v248 offset:34816
	ds_read_b128 v[172:175], v248 offset:35840
	ds_read_b128 v[176:179], v248 offset:36864
	ds_read_b128 v[180:183], v248 offset:37888
	ds_read_b128 v[184:187], v248 offset:38912
	ds_read_b128 v[188:191], v248 offset:39936
	global_load_lds_dwordx4 v[202:203], off
	v_lshl_add_u64 v[202:203], s[54:55], 0, v[214:215]
	s_mov_b32 m0, s90
	s_nop 0
	global_load_lds_dwordx4 v[202:203], off
	s_waitcnt vmcnt(8)
	s_waitcnt lgkmcnt(0)
	s_barrier
	s_setprio 1
	s_waitcnt lgkmcnt(0)
	v_mfma_f32_16x16x32_bf16 v[132:135], v[104:107], v[160:163], v[132:135]
	v_mfma_f32_16x16x32_bf16 v[128:131], v[136:139], v[160:163], v[128:131]
	v_mfma_f32_16x16x32_bf16 v[116:119], v[104:107], v[168:171], v[116:119]
	v_mfma_f32_16x16x32_bf16 v[108:111], v[136:139], v[168:171], v[108:111]
	v_mfma_f32_16x16x32_bf16 v[96:99], v[104:107], v[176:179], v[96:99]
	v_mfma_f32_16x16x32_bf16 v[88:91], v[136:139], v[176:179], v[88:91]
	v_mfma_f32_16x16x32_bf16 v[80:83], v[104:107], v[184:187], v[80:83]
	v_mfma_f32_16x16x32_bf16 v[72:75], v[136:139], v[184:187], v[72:75]
	v_mfma_f32_16x16x32_bf16 v[132:135], v[112:115], v[164:167], v[132:135]
	v_mfma_f32_16x16x32_bf16 v[128:131], v[140:143], v[164:167], v[128:131]
	v_mfma_f32_16x16x32_bf16 v[116:119], v[112:115], v[172:175], v[116:119]
	v_mfma_f32_16x16x32_bf16 v[108:111], v[140:143], v[172:175], v[108:111]
	v_mfma_f32_16x16x32_bf16 v[96:99], v[112:115], v[180:183], v[96:99]
	v_mfma_f32_16x16x32_bf16 v[88:91], v[140:143], v[180:183], v[88:91]
	v_mfma_f32_16x16x32_bf16 v[80:83], v[112:115], v[188:191], v[80:83]
	v_mfma_f32_16x16x32_bf16 v[72:75], v[140:143], v[188:191], v[72:75]
	s_setprio 0
	s_setprio 1
	v_mfma_f32_16x16x32_bf16 v[124:127], v[144:147], v[160:163], v[124:127]
	v_mfma_f32_16x16x32_bf16 v[120:123], v[152:155], v[160:163], v[120:123]
	v_mfma_f32_16x16x32_bf16 v[100:103], v[144:147], v[168:171], v[100:103]
	v_mfma_f32_16x16x32_bf16 v[92:95], v[152:155], v[168:171], v[92:95]
	v_mfma_f32_16x16x32_bf16 v[84:87], v[144:147], v[176:179], v[84:87]
	v_mfma_f32_16x16x32_bf16 v[76:79], v[152:155], v[176:179], v[76:79]
	v_mfma_f32_16x16x32_bf16 v[68:71], v[144:147], v[184:187], v[68:71]
	v_mfma_f32_16x16x32_bf16 v[64:67], v[152:155], v[184:187], v[64:67]
	v_mfma_f32_16x16x32_bf16 v[124:127], v[148:151], v[164:167], v[124:127]
	v_mfma_f32_16x16x32_bf16 v[120:123], v[156:159], v[164:167], v[120:123]
	v_mfma_f32_16x16x32_bf16 v[100:103], v[148:151], v[172:175], v[100:103]
	v_mfma_f32_16x16x32_bf16 v[92:95], v[156:159], v[172:175], v[92:95]
	v_mfma_f32_16x16x32_bf16 v[84:87], v[148:151], v[180:183], v[84:87]
	v_mfma_f32_16x16x32_bf16 v[76:79], v[156:159], v[180:183], v[76:79]
	v_mfma_f32_16x16x32_bf16 v[68:71], v[148:151], v[188:191], v[68:71]
	v_mfma_f32_16x16x32_bf16 v[64:67], v[156:159], v[188:191], v[64:67]
	s_setprio 0
	s_barrier
	s_add_i32 s52, s52, s50
	v_lshl_add_u64 v[194:195], v[194:195], 0, s[12:13]
	s_mov_b32 m0, s52
	ds_read_b128 v[160:163], v248 offset:49152
	ds_read_b128 v[164:167], v248 offset:50176
	ds_read_b128 v[168:171], v248 offset:51200
	ds_read_b128 v[172:175], v248 offset:52224
	ds_read_b128 v[176:179], v248 offset:53248
	ds_read_b128 v[180:183], v248 offset:54272
	ds_read_b128 v[184:187], v248 offset:55296
	ds_read_b128 v[188:191], v248 offset:56320
	global_load_lds_dwordx4 v[194:195], off
	s_add_i32 m0, s52, 0x2000
	s_add_u32 s46, s46, 0x40080
	v_lshl_add_u64 v[194:195], v[196:197], 0, s[12:13]
	s_addc_u32 s47, s47, 0
	s_add_i32 s52, s53, s50
	global_load_lds_dwordx4 v[194:195], off
	v_lshl_add_u64 v[194:195], s[46:47], 0, v[216:217]
	s_mov_b32 m0, s52
	s_nop 0
	global_load_lds_dwordx4 v[194:195], off
	v_lshl_add_u64 v[194:195], s[46:47], 0, v[212:213]
	s_add_i32 m0, s52, 0x2000
	s_nop 0
	global_load_lds_dwordx4 v[194:195], off
	v_lshl_add_u64 v[194:195], v[198:199], 0, s[12:13]
	s_mov_b32 m0, s66
	s_nop 0
	global_load_lds_dwordx4 v[194:195], off
	v_lshl_add_u64 v[194:195], v[200:201], 0, s[12:13]
	s_mov_b32 m0, s86
	s_nop 0
	global_load_lds_dwordx4 v[194:195], off
	s_waitcnt vmcnt(8)
	s_waitcnt lgkmcnt(0)
	s_barrier
; __device__ __forceinline__ unsigned cvt_pk_bf16(float lo, float hi) { const cvt_f32x2_t v = {lo, hi}; const cvt_bf16x2_t b = __builtin_convertvector(v, cvt_bf16x2_t); return __builtin_bit_cast(unsigned, b); }
; #define PG8_MMA(ai, bj, At, Bt) do { __builtin_amdgcn_s_setprio(1); _Pragma("unroll") for (int m = 0; m < 4; ++m) _Pragma("unroll") for (int n = 0; n < 2; ++n) _Pragma("unroll") for (int k = 0; k < 2; ++k) \
;         acc[ai][bj][m][n] = __builtin_amdgcn_mfma_f32_16x16x32_bf16(Bt[n][k], At[m][k], acc[ai][bj][m][n], 0, 0, 0); __builtin_amdgcn_s_setprio(0); } while (0)
; #define PG8_WAIT_V(n) asm volatile("s_waitcnt vmcnt(" #n ")" ::: "memory")
; #define PG8_WAIT_L(n) asm volatile("s_waitcnt lgkmcnt(" #n ")" ::: "memory")
; #define PG8_BAR __builtin_amdgcn_s_barrier()
; #define PG8_SCHED __builtin_amdgcn_sched_barrier(0)
; __device__ __forceinline__ float bf_lo(unsigned u) { return __uint_as_float(u << 16); }
; __device__ __forceinline__ float bf_hi(unsigned u) { return __uint_as_float(u & 0xffff0000u); }
; template <class Epi, class Sched, bool ALIGN_EPI>
; __device__ __forceinline__ void gemm_phase(LAS unsigned char* lds, const Gemm g, const Sched& S, const Epi& E) {
;     ...
;             PG8_WAIT_V(8); PG8_WAIT_L(0); PG8_BAR; PG8_MMA(1, 0, At, B0); PG8_MMA(1, 1, At, B1); PG8_BAR; PG8_SCHED;
;         }
;         if constexpr (ALIGN_EPI) { if (wr == 0) PG8_BAR; }
; __global__ void __launch_bounds__(512, 2) fwd_kernel(Args args) {
;     ...
;                         for (int e = 0; e < 8; ++e) { const int row = pm * 256 + r0_ + 8 * e; const float rs = rsv[e]; u32x4 w = wv[e];
;                             w.x = cvt_pk_bf16(bf_lo(w.x) * rs, bf_hi(w.x) * rs); w.y = cvt_pk_bf16(bf_lo(w.y) * rs, bf_hi(w.y) * rs);
;                             w.z = cvt_pk_bf16(bf_lo(w.z) * rs, bf_hi(w.z) * rs); w.w = cvt_pk_bf16(bf_lo(w.w) * rs, bf_hi(w.w) * rs);
	s_setprio 1
	s_waitcnt lgkmcnt(0)
	v_mfma_f32_16x16x32_bf16 v[60:63], v[104:107], v[160:163], v[60:63]
	v_mfma_f32_16x16x32_bf16 v[56:59], v[136:139], v[160:163], v[56:59]
	v_mfma_f32_16x16x32_bf16 v[44:47], v[104:107], v[168:171], v[44:47]
	v_mfma_f32_16x16x32_bf16 v[40:43], v[136:139], v[168:171], v[40:43]
	v_mfma_f32_16x16x32_bf16 v[32:35], v[104:107], v[176:179], v[32:35]
	v_mfma_f32_16x16x32_bf16 v[24:27], v[136:139], v[176:179], v[24:27]
	v_mfma_f32_16x16x32_bf16 v[16:19], v[104:107], v[184:187], v[16:19]
	v_mfma_f32_16x16x32_bf16 v[8:11], v[136:139], v[184:187], v[8:11]
	v_mfma_f32_16x16x32_bf16 v[60:63], v[112:115], v[164:167], v[60:63]
	v_mfma_f32_16x16x32_bf16 v[56:59], v[140:143], v[164:167], v[56:59]
	v_mfma_f32_16x16x32_bf16 v[44:47], v[112:115], v[172:175], v[44:47]
	v_mfma_f32_16x16x32_bf16 v[40:43], v[140:143], v[172:175], v[40:43]
	v_mfma_f32_16x16x32_bf16 v[32:35], v[112:115], v[180:183], v[32:35]
	v_mfma_f32_16x16x32_bf16 v[24:27], v[140:143], v[180:183], v[24:27]
	v_mfma_f32_16x16x32_bf16 v[16:19], v[112:115], v[188:191], v[16:19]
	v_mfma_f32_16x16x32_bf16 v[8:11], v[140:143], v[188:191], v[8:11]
	s_setprio 0
	s_setprio 1
	v_mfma_f32_16x16x32_bf16 v[52:55], v[144:147], v[160:163], v[52:55]
	v_mfma_f32_16x16x32_bf16 v[48:51], v[152:155], v[160:163], v[48:51]
	v_mfma_f32_16x16x32_bf16 v[36:39], v[144:147], v[168:171], v[36:39]
	v_mfma_f32_16x16x32_bf16 v[28:31], v[152:155], v[168:171], v[28:31]
	v_mfma_f32_16x16x32_bf16 v[20:23], v[144:147], v[176:179], v[20:23]
	v_mfma_f32_16x16x32_bf16 v[12:15], v[152:155], v[176:179], v[12:15]
	v_mfma_f32_16x16x32_bf16 v[4:7], v[144:147], v[184:187], v[4:7]
	v_mfma_f32_16x16x32_bf16 v[0:3], v[152:155], v[184:187], v[0:3]
	v_mfma_f32_16x16x32_bf16 v[52:55], v[148:151], v[164:167], v[52:55]
	v_mfma_f32_16x16x32_bf16 v[48:51], v[156:159], v[164:167], v[48:51]
	v_mfma_f32_16x16x32_bf16 v[36:39], v[148:151], v[172:175], v[36:39]
	v_mfma_f32_16x16x32_bf16 v[28:31], v[156:159], v[172:175], v[28:31]
	v_mfma_f32_16x16x32_bf16 v[20:23], v[148:151], v[180:183], v[20:23]
	v_mfma_f32_16x16x32_bf16 v[12:15], v[156:159], v[180:183], v[12:15]
	v_mfma_f32_16x16x32_bf16 v[4:7], v[148:151], v[188:191], v[4:7]
	v_mfma_f32_16x16x32_bf16 v[0:3], v[156:159], v[188:191], v[0:3]
	s_setprio 0
	s_barrier
	s_add_i32 s92, s92, 2
	s_add_u32 s44, s44, 0x100
	s_addc_u32 s45, s45, 0
	s_add_u32 s64, s64, 0x100
	s_addc_u32 s65, s65, 0
	s_cmp_gt_u32 s92, 13
	s_cbranch_scc0 .LBB0_316
	s_and_b32 vcc_lo, s5, 1
	s_mul_i32 vcc_lo, vcc_lo, 0x3800
	s_and_b32 vcc_hi, s40, 0x100
	s_add_i32 vcc_lo, vcc_lo, 0x20000
	s_add_i32 vcc_lo, vcc_lo, vcc_hi
	v_lshl_add_u32 v176, v211, 2, vcc_lo
	ds_read_b32 v160, v176
	ds_read_b32 v162, v176 offset:64
	ds_read_b32 v164, v176 offset:128
	ds_read_b32 v166, v176 offset:192
	ds_read_b32 v168, v176 offset:512
	ds_read_b32 v170, v176 offset:576
	ds_read_b32 v172, v176 offset:640
	ds_read_b32 v174, v176 offset:704
	s_waitcnt lgkmcnt(0)
	v_pk_mul_f32 v[120:121], v[160:161], v[120:121] op_sel_hi:[0,1]
	v_pk_mul_f32 v[122:123], v[160:161], v[122:123] op_sel_hi:[0,1]
	v_pk_mul_f32 v[124:125], v[160:161], v[124:125] op_sel_hi:[0,1]
	v_pk_mul_f32 v[126:127], v[160:161], v[126:127] op_sel_hi:[0,1]
	v_pk_mul_f32 v[128:129], v[160:161], v[128:129] op_sel_hi:[0,1]
	v_pk_mul_f32 v[130:131], v[160:161], v[130:131] op_sel_hi:[0,1]
	v_pk_mul_f32 v[132:133], v[160:161], v[132:133] op_sel_hi:[0,1]
	v_pk_mul_f32 v[134:135], v[160:161], v[134:135] op_sel_hi:[0,1]
	v_pk_mul_f32 v[92:93], v[162:163], v[92:93] op_sel_hi:[0,1]
	v_pk_mul_f32 v[94:95], v[162:163], v[94:95] op_sel_hi:[0,1]
	v_pk_mul_f32 v[100:101], v[162:163], v[100:101] op_sel_hi:[0,1]
	v_pk_mul_f32 v[102:103], v[162:163], v[102:103] op_sel_hi:[0,1]
	v_pk_mul_f32 v[108:109], v[162:163], v[108:109] op_sel_hi:[0,1]
	v_pk_mul_f32 v[110:111], v[162:163], v[110:111] op_sel_hi:[0,1]
	v_pk_mul_f32 v[116:117], v[162:163], v[116:117] op_sel_hi:[0,1]
	v_pk_mul_f32 v[118:119], v[162:163], v[118:119] op_sel_hi:[0,1]
	v_pk_mul_f32 v[76:77], v[164:165], v[76:77] op_sel_hi:[0,1]
	v_pk_mul_f32 v[78:79], v[164:165], v[78:79] op_sel_hi:[0,1]
	v_pk_mul_f32 v[84:85], v[164:165], v[84:85] op_sel_hi:[0,1]
	v_pk_mul_f32 v[86:87], v[164:165], v[86:87] op_sel_hi:[0,1]
	v_pk_mul_f32 v[88:89], v[164:165], v[88:89] op_sel_hi:[0,1]
	v_pk_mul_f32 v[90:91], v[164:165], v[90:91] op_sel_hi:[0,1]
	v_pk_mul_f32 v[96:97], v[164:165], v[96:97] op_sel_hi:[0,1]
	v_pk_mul_f32 v[98:99], v[164:165], v[98:99] op_sel_hi:[0,1]
	v_pk_mul_f32 v[64:65], v[166:167], v[64:65] op_sel_hi:[0,1]
	v_pk_mul_f32 v[66:67], v[166:167], v[66:67] op_sel_hi:[0,1]
	v_pk_mul_f32 v[68:69], v[166:167], v[68:69] op_sel_hi:[0,1]
	v_pk_mul_f32 v[70:71], v[166:167], v[70:71] op_sel_hi:[0,1]
	v_pk_mul_f32 v[72:73], v[166:167], v[72:73] op_sel_hi:[0,1]
	v_pk_mul_f32 v[74:75], v[166:167], v[74:75] op_sel_hi:[0,1]
	v_pk_mul_f32 v[80:81], v[166:167], v[80:81] op_sel_hi:[0,1]
	v_pk_mul_f32 v[82:83], v[166:167], v[82:83] op_sel_hi:[0,1]
	v_pk_mul_f32 v[48:49], v[168:169], v[48:49] op_sel_hi:[0,1]
	v_pk_mul_f32 v[50:51], v[168:169], v[50:51] op_sel_hi:[0,1]
	v_pk_mul_f32 v[52:53], v[168:169], v[52:53] op_sel_hi:[0,1]
	v_pk_mul_f32 v[54:55], v[168:169], v[54:55] op_sel_hi:[0,1]
	v_pk_mul_f32 v[56:57], v[168:169], v[56:57] op_sel_hi:[0,1]
	v_pk_mul_f32 v[58:59], v[168:169], v[58:59] op_sel_hi:[0,1]
	v_pk_mul_f32 v[60:61], v[168:169], v[60:61] op_sel_hi:[0,1]
	v_pk_mul_f32 v[62:63], v[168:169], v[62:63] op_sel_hi:[0,1]
	v_pk_mul_f32 v[28:29], v[170:171], v[28:29] op_sel_hi:[0,1]
	v_pk_mul_f32 v[30:31], v[170:171], v[30:31] op_sel_hi:[0,1]
	v_pk_mul_f32 v[36:37], v[170:171], v[36:37] op_sel_hi:[0,1]
	v_pk_mul_f32 v[38:39], v[170:171], v[38:39] op_sel_hi:[0,1]
	v_pk_mul_f32 v[40:41], v[170:171], v[40:41] op_sel_hi:[0,1]
	v_pk_mul_f32 v[42:43], v[170:171], v[42:43] op_sel_hi:[0,1]
	v_pk_mul_f32 v[44:45], v[170:171], v[44:45] op_sel_hi:[0,1]
	v_pk_mul_f32 v[46:47], v[170:171], v[46:47] op_sel_hi:[0,1]
	v_pk_mul_f32 v[12:13], v[172:173], v[12:13] op_sel_hi:[0,1]
	v_pk_mul_f32 v[14:15], v[172:173], v[14:15] op_sel_hi:[0,1]
	v_pk_mul_f32 v[20:21], v[172:173], v[20:21] op_sel_hi:[0,1]
	v_pk_mul_f32 v[22:23], v[172:173], v[22:23] op_sel_hi:[0,1]
	v_pk_mul_f32 v[24:25], v[172:173], v[24:25] op_sel_hi:[0,1]
	v_pk_mul_f32 v[26:27], v[172:173], v[26:27] op_sel_hi:[0,1]
	v_pk_mul_f32 v[32:33], v[172:173], v[32:33] op_sel_hi:[0,1]
	v_pk_mul_f32 v[34:35], v[172:173], v[34:35] op_sel_hi:[0,1]
	v_pk_mul_f32 v[0:1], v[174:175], v[0:1] op_sel_hi:[0,1]
	v_pk_mul_f32 v[2:3], v[174:175], v[2:3] op_sel_hi:[0,1]
	v_pk_mul_f32 v[4:5], v[174:175], v[4:5] op_sel_hi:[0,1]
	v_pk_mul_f32 v[6:7], v[174:175], v[6:7] op_sel_hi:[0,1]
	v_pk_mul_f32 v[8:9], v[174:175], v[8:9] op_sel_hi:[0,1]
	v_pk_mul_f32 v[10:11], v[174:175], v[10:11] op_sel_hi:[0,1]
	v_pk_mul_f32 v[16:17], v[174:175], v[16:17] op_sel_hi:[0,1]
	v_pk_mul_f32 v[18:19], v[174:175], v[18:19] op_sel_hi:[0,1]
	s_and_b64 vcc, exec, s[22:23]
	s_cbranch_vccz .LBB0_319
	s_barrier

; __device__ __forceinline__ unsigned cvt_pk_bf16(float lo, float hi) { const cvt_f32x2_t v = {lo, hi}; const cvt_bf16x2_t b = __builtin_convertvector(v, cvt_bf16x2_t); return __builtin_bit_cast(unsigned, b); }
; __device__ __forceinline__ float bf_lo(unsigned u) { return __uint_as_float(u << 16); }
; __device__ __forceinline__ float bf_hi(unsigned u) { return __uint_as_float(u & 0xffff0000u); }
; __device__ __forceinline__ float rsq(float x) { return __builtin_amdgcn_rsqf(x); }
; __device__ __forceinline__ float sum4(f32x4 v) { return (v[0] + v[1]) + (v[2] + v[3]); }
; #define STATS WSP(float, WS_STATS)
; __global__ void __launch_bounds__(512, 2) fwd_kernel(Args args) {
;     ...
;                 __builtin_amdgcn_fence(__ATOMIC_RELEASE, "workgroup"); __syncthreads(); __builtin_amdgcn_fence(__ATOMIC_ACQUIRE, "workgroup");
;                 for (int pm = bid; pm < 256; pm += G)
;                     for (int r0_ = wave; r0_ < 256; r0_ += 64) {
;                         u32x4 wv[8]; float rsv[8];
;                         const float* stp = STATS; bf16_t* mixp = MIX;
; #pragma unroll
;                         for (int e = 0; e < 8; ++e) { const int row = pm * 256 + r0_ + 8 * e;
;                             const f32x4* sp = (const f32x4*)(stp + (size_t)row * 8);
;                             rsv[e] = rsq((sum4(sp[0]) + sum4(sp[1])) * (1.0f / SW) + EPS);
;                             wv[e] = *((const u32x4*)(mixp + (size_t)row * DM + AW) + lane); }
;                         asm volatile("" ::: "memory");
; #pragma unroll
;                         for (int e = 0; e < 8; ++e) { const int row = pm * 256 + r0_ + 8 * e; const float rs = rsv[e]; u32x4 w = wv[e];
;                             w.x = cvt_pk_bf16(bf_lo(w.x) * rs, bf_hi(w.x) * rs); w.y = cvt_pk_bf16(bf_lo(w.y) * rs, bf_hi(w.y) * rs);
;                             w.z = cvt_pk_bf16(bf_lo(w.z) * rs, bf_hi(w.z) * rs); w.w = cvt_pk_bf16(bf_lo(w.w) * rs, bf_hi(w.w) * rs);
;                             *((u32x4*)(mixp + (size_t)row * DM + AW) + lane) = w; }
;                     }
.LBB0_411:
	s_and_b64 vcc, exec, s[42:43]
	s_waitcnt lgkmcnt(0)
	s_barrier
	s_branch .LBB0_417
